# FFN-up: first K-iteration of each tile peeled (C=0 MFMAs replace the accumulator zero-fill; first two vmcnt waits only on the first tile)
# speedup vs baseline: 1.0052x; 1.0052x over previous
; #define PG8_STAGE(bufoff, gbase, voff) do { _Pragma("unroll") for (int _i = 0; _i < 2; ++_i) \
;         __builtin_amdgcn_global_load_lds((const unsigned*)((const char*)(gbase) + (voff)[_i]), (PG8_LAS unsigned*)(lds + (bufoff) + ldsw + _i * 8192), 16, 0, 0); } while (0)
; #define PG8_LDA(dst, b, h) do { _Pragma("unroll") for (int m = 0; m < 4; ++m) _Pragma("unroll") for (int k = 0; k < 2; ++k) dst[m][k] = *(const PG8_LAS bf16x8*)(lds + PG8_SA(b, h) + aoff + m * 2048 + k * 1024); } while (0)
; #define PG8_LDB(dst, b, h) do { _Pragma("unroll") for (int n = 0; n < 2; ++n) _Pragma("unroll") for (int k = 0; k < 2; ++k) dst[n][k] = *(const PG8_LAS bf16x8*)(lds + PG8_SB(b, h) + boff + n * 2048 + k * 1024); } while (0)
; #define PG8_MMA(ai, bj, At, Bt) do { __builtin_amdgcn_s_setprio(1); _Pragma("unroll") for (int m = 0; m < 4; ++m) _Pragma("unroll") for (int n = 0; n < 2; ++n) _Pragma("unroll") for (int k = 0; k < 2; ++k) \
;         acc[ai][bj][m][n] = __builtin_amdgcn_mfma_f32_16x16x32_bf16(Bt[n][k], At[m][k], acc[ai][bj][m][n], 0, 0, 0); __builtin_amdgcn_s_setprio(0); } while (0)
; #define PG8_WAIT_V(n) asm volatile("s_waitcnt vmcnt(" #n ")" ::: "memory")
; #define PG8_WAIT_L(n) asm volatile("s_waitcnt lgkmcnt(" #n ")" ::: "memory")
; #define PG8_BAR __builtin_amdgcn_s_barrier()
; #define PG8_SCHED __builtin_amdgcn_sched_barrier(0)
; template <class Epi, class Sched, bool ALIGN_EPI = false, bool SP2 = false>
; __device__ __forceinline__ void gemm_phase(PG8_LAS unsigned char* lds, const Gemm g, const Sched& S, const Epi& E, const int tid_) {
;     ...
;                 for (int n = 0; n < 2; ++n) acc[a][b][m][n] = (f32x4){0.f, 0.f, 0.f, 0.f};
;     ...
;             PG8_LDB(B0, 0, 0); PG8_LDB(B1, 0, 1); PG8_SCHED; PG8_LDA(At, 0, 0); PG8_STAGE(PG8_SA(1, 1), a1 + hstep, voffA);
;             PG8_WAIT_V(8); PG8_WAIT_L(0); PG8_BAR; PG8_MMA(0, 0, At, B0); PG8_MMA(0, 1, At, B1); PG8_BAR; PG8_SCHED;
;             PG8_LDA(At, 0, 1); PG8_STAGE(PG8_SB(0, 0), b2, voffB); PG8_STAGE(PG8_SB(0, 1), b2 + hstepB, voffB); PG8_STAGE(PG8_SA(0, 0), a2, voffA);
;             PG8_WAIT_V(8); PG8_WAIT_L(0); PG8_BAR; PG8_MMA(1, 0, At, B0); PG8_MMA(1, 1, At, B1); PG8_BAR; PG8_SCHED;
.LBB0_23:
	s_ashr_i32 s17, s16, 31
	s_lshl_b64 s[2:3], s[16:17], 19
	s_add_u32 s18, s78, s2
	s_addc_u32 s19, s79, s3
	s_and_b64 s[2:3], s[6:7], exec
	s_cselect_b32 s2, s19, s25
	s_cselect_b32 s3, s18, s24
	s_ashr_i32 s15, s14, 31
	s_lshl_b64 s[20:21], s[14:15], 19
	s_add_u32 s20, s30, s20
	s_addc_u32 s21, s31, s21
	s_and_b64 s[28:29], s[6:7], exec
	s_cselect_b32 s15, s21, s27
	s_cselect_b32 s17, s20, s26
	s_add_u32 s24, s24, 0x40080
	s_addc_u32 s25, s25, 0
	s_add_u32 s55, s26, 0x100
	s_addc_u32 s56, s27, 0
	s_mov_b32 s57, -2
	v_add_u32_e32 v154, s23, v163
	v_add_u32_e32 v174, s37, v163
	ds_read_b128 v[132:135], v154
	ds_read_b128 v[146:149], v154 offset:1024
	ds_read_b128 v[150:153], v154 offset:2048
	ds_read_b128 v[154:157], v154 offset:3072
	ds_read_b128 v[158:161], v174
	ds_read_b128 v[166:169], v174 offset:1024
	ds_read_b128 v[170:173], v174 offset:2048
	ds_read_b128 v[174:177], v174 offset:3072
	s_add_u32 s26, s24, 0xfffc0080
	s_addc_u32 s27, s25, -1
	s_cmp_eq_u32 s57, 12
	s_cselect_b32 s29, s2, s27
	s_cselect_b32 s28, s3, s26
	s_cselect_b32 s27, s15, s56
	s_cselect_b32 s26, s17, s55
	v_lshl_add_u64 v[178:179], s[24:25], 0, v[142:143]
	s_add_i32 m0, s40, 0xc000
	ds_read_b128 v[188:191], v165
	ds_read_b128 v[192:195], v165 offset:1024
	ds_read_b128 v[196:199], v165 offset:2048
	ds_read_b128 v[200:203], v165 offset:3072
	ds_read_b128 v[204:207], v165 offset:4096
	ds_read_b128 v[208:211], v165 offset:5120
	ds_read_b128 v[212:215], v165 offset:6144
	ds_read_b128 v[216:219], v165 offset:7168
	global_load_lds_dwordx4 v[178:179], off
	v_lshl_add_u64 v[178:179], s[24:25], 0, v[144:145]
	s_add_i32 m0, s40, 0xe000
	s_nop 0
	global_load_lds_dwordx4 v[178:179], off
	s_cmp_lg_u32 s53, 1
	s_cbranch_scc1 .Lpeel1_w1
	s_waitcnt vmcnt(8)
.Lpeel1_w1:
	s_waitcnt lgkmcnt(0)
	s_barrier
	s_setprio 1
	s_waitcnt lgkmcnt(0)
	v_mfma_f32_16x16x32_bf16 v[128:131], v[132:135], v[188:191], 0
	v_mfma_f32_16x16x32_bf16 v[120:123], v[150:153], v[188:191], 0
	v_mfma_f32_16x16x32_bf16 v[112:115], v[132:135], v[196:199], 0
	v_mfma_f32_16x16x32_bf16 v[104:107], v[150:153], v[196:199], 0
	v_mfma_f32_16x16x32_bf16 v[96:99], v[132:135], v[204:207], 0
	v_mfma_f32_16x16x32_bf16 v[88:91], v[150:153], v[204:207], 0
	v_mfma_f32_16x16x32_bf16 v[80:83], v[132:135], v[212:215], 0
	v_mfma_f32_16x16x32_bf16 v[72:75], v[150:153], v[212:215], 0
	v_mfma_f32_16x16x32_bf16 v[128:131], v[146:149], v[192:195], v[128:131]
	v_mfma_f32_16x16x32_bf16 v[120:123], v[154:157], v[192:195], v[120:123]
	v_mfma_f32_16x16x32_bf16 v[112:115], v[146:149], v[200:203], v[112:115]
	v_mfma_f32_16x16x32_bf16 v[104:107], v[154:157], v[200:203], v[104:107]
	v_mfma_f32_16x16x32_bf16 v[96:99], v[146:149], v[208:211], v[96:99]
	v_mfma_f32_16x16x32_bf16 v[88:91], v[154:157], v[208:211], v[88:91]
	v_mfma_f32_16x16x32_bf16 v[80:83], v[146:149], v[216:219], v[80:83]
	v_mfma_f32_16x16x32_bf16 v[72:75], v[154:157], v[216:219], v[72:75]
	s_setprio 0
	s_setprio 1
	v_mfma_f32_16x16x32_bf16 v[124:127], v[158:161], v[188:191], 0
	v_mfma_f32_16x16x32_bf16 v[116:119], v[170:173], v[188:191], 0
	v_mfma_f32_16x16x32_bf16 v[108:111], v[158:161], v[196:199], 0
	v_mfma_f32_16x16x32_bf16 v[100:103], v[170:173], v[196:199], 0
	v_mfma_f32_16x16x32_bf16 v[92:95], v[158:161], v[204:207], 0
	v_mfma_f32_16x16x32_bf16 v[84:87], v[170:173], v[204:207], 0
	v_mfma_f32_16x16x32_bf16 v[76:79], v[158:161], v[212:215], 0
	v_mfma_f32_16x16x32_bf16 v[68:71], v[170:173], v[212:215], 0
	v_mfma_f32_16x16x32_bf16 v[124:127], v[166:169], v[192:195], v[124:127]
	v_mfma_f32_16x16x32_bf16 v[116:119], v[174:177], v[192:195], v[116:119]
	v_mfma_f32_16x16x32_bf16 v[108:111], v[166:169], v[200:203], v[108:111]
	v_mfma_f32_16x16x32_bf16 v[100:103], v[174:177], v[200:203], v[100:103]
	v_mfma_f32_16x16x32_bf16 v[92:95], v[166:169], v[208:211], v[92:95]
	v_mfma_f32_16x16x32_bf16 v[84:87], v[174:177], v[208:211], v[84:87]
	v_mfma_f32_16x16x32_bf16 v[76:79], v[166:169], v[216:219], v[76:79]
	v_mfma_f32_16x16x32_bf16 v[68:71], v[174:177], v[216:219], v[68:71]
	s_setprio 0
	s_barrier
	s_mov_b32 m0, s35
	v_lshl_add_u64 v[178:179], s[26:27], 0, v[2:3]
	s_add_u32 s58, s26, 0x40000
	ds_read_b128 v[188:191], v165 offset:16384
	ds_read_b128 v[192:195], v165 offset:17408
	ds_read_b128 v[196:199], v165 offset:18432
	ds_read_b128 v[200:203], v165 offset:19456
	ds_read_b128 v[204:207], v165 offset:20480
	ds_read_b128 v[208:211], v165 offset:21504
	ds_read_b128 v[212:215], v165 offset:22528
	ds_read_b128 v[216:219], v165 offset:23552
	global_load_lds_dwordx4 v[178:179], off
	v_lshl_add_u64 v[220:221], s[26:27], 0, v[0:1]
	s_mov_b32 m0, s36
	s_addc_u32 s59, s27, 0
	global_load_lds_dwordx4 v[220:221], off
	v_lshl_add_u64 v[222:223], s[58:59], 0, v[2:3]
	s_mov_b32 m0, s38
	v_lshl_add_u64 v[224:225], s[28:29], 0, v[136:137]
	global_load_lds_dwordx4 v[222:223], off
	v_lshl_add_u64 v[222:223], s[58:59], 0, v[0:1]
	s_mov_b32 m0, s39
	s_nop 0
	global_load_lds_dwordx4 v[222:223], off
	v_lshl_add_u64 v[222:223], s[28:29], 0, v[138:139]
	s_mov_b32 m0, s40
	s_nop 0
	global_load_lds_dwordx4 v[222:223], off
	s_mov_b32 m0, s41
	s_nop 0
	global_load_lds_dwordx4 v[224:225], off
	s_cmp_lg_u32 s53, 1
	s_cbranch_scc1 .Lpeel1_w2
	s_waitcnt vmcnt(8)
; #define PG8_STAGE(bufoff, gbase, voff) do { _Pragma("unroll") for (int _i = 0; _i < 2; ++_i) \
;         __builtin_amdgcn_global_load_lds((const unsigned*)((const char*)(gbase) + (voff)[_i]), (PG8_LAS unsigned*)(lds + (bufoff) + ldsw + _i * 8192), 16, 0, 0); } while (0)
; #define PG8_LDA(dst, b, h) do { _Pragma("unroll") for (int m = 0; m < 4; ++m) _Pragma("unroll") for (int k = 0; k < 2; ++k) dst[m][k] = *(const PG8_LAS bf16x8*)(lds + PG8_SA(b, h) + aoff + m * 2048 + k * 1024); } while (0)
; #define PG8_LDB(dst, b, h) do { _Pragma("unroll") for (int n = 0; n < 2; ++n) _Pragma("unroll") for (int k = 0; k < 2; ++k) dst[n][k] = *(const PG8_LAS bf16x8*)(lds + PG8_SB(b, h) + boff + n * 2048 + k * 1024); } while (0)
; #define PG8_MMA(ai, bj, At, Bt) do { __builtin_amdgcn_s_setprio(1); _Pragma("unroll") for (int m = 0; m < 4; ++m) _Pragma("unroll") for (int n = 0; n < 2; ++n) _Pragma("unroll") for (int k = 0; k < 2; ++k) \
;         acc[ai][bj][m][n] = __builtin_amdgcn_mfma_f32_16x16x32_bf16(Bt[n][k], At[m][k], acc[ai][bj][m][n], 0, 0, 0); __builtin_amdgcn_s_setprio(0); } while (0)
; #define PG8_WAIT_V(n) asm volatile("s_waitcnt vmcnt(" #n ")" ::: "memory")
; #define PG8_WAIT_L(n) asm volatile("s_waitcnt lgkmcnt(" #n ")" ::: "memory")
; #define PG8_BAR __builtin_amdgcn_s_barrier()
; #define PG8_SCHED __builtin_amdgcn_sched_barrier(0)
; template <class Epi, class Sched, bool ALIGN_EPI = false, bool SP2 = false>
; __device__ __forceinline__ void gemm_phase(PG8_LAS unsigned char* lds, const Gemm g, const Sched& S, const Epi& E, const int tid_) {
;     ...
;             PG8_WAIT_V(8); PG8_WAIT_L(0); PG8_BAR; PG8_MMA(0, 0, At, B0); PG8_MMA(0, 1, At, B1); PG8_BAR; PG8_SCHED;
;             PG8_LDA(At, 0, 1); PG8_STAGE(PG8_SB(0, 0), b2, voffB); PG8_STAGE(PG8_SB(0, 1), b2 + hstepB, voffB); PG8_STAGE(PG8_SA(0, 0), a2, voffA);
;             PG8_WAIT_V(8); PG8_WAIT_L(0); PG8_BAR; PG8_MMA(1, 0, At, B0); PG8_MMA(1, 1, At, B1); PG8_BAR; PG8_SCHED;
;             PG8_LDB(B0, 1, 0); PG8_LDB(B1, 1, 1); PG8_SCHED; PG8_LDA(At, 1, 0); PG8_STAGE(PG8_SA(0, 1), a2 + hstep, voffA);
;             PG8_WAIT_V(8); PG8_WAIT_L(0); PG8_BAR; PG8_MMA(0, 0, At, B0); PG8_MMA(0, 1, At, B1); PG8_BAR; PG8_SCHED;
.Lpeel1_w2:
	s_waitcnt lgkmcnt(0)
	s_barrier
	s_setprio 1
	s_waitcnt lgkmcnt(0)
	v_mfma_f32_16x16x32_bf16 v[64:67], v[132:135], v[188:191], 0
	v_mfma_f32_16x16x32_bf16 v[56:59], v[150:153], v[188:191], 0
	v_mfma_f32_16x16x32_bf16 v[48:51], v[132:135], v[196:199], 0
	v_mfma_f32_16x16x32_bf16 v[40:43], v[150:153], v[196:199], 0
	v_mfma_f32_16x16x32_bf16 v[32:35], v[132:135], v[204:207], 0
	v_mfma_f32_16x16x32_bf16 v[24:27], v[150:153], v[204:207], 0
	v_mfma_f32_16x16x32_bf16 v[16:19], v[132:135], v[212:215], 0
	v_mfma_f32_16x16x32_bf16 v[8:11], v[150:153], v[212:215], 0
	v_mfma_f32_16x16x32_bf16 v[64:67], v[146:149], v[192:195], v[64:67]
	v_mfma_f32_16x16x32_bf16 v[56:59], v[154:157], v[192:195], v[56:59]
	v_mfma_f32_16x16x32_bf16 v[48:51], v[146:149], v[200:203], v[48:51]
	v_mfma_f32_16x16x32_bf16 v[40:43], v[154:157], v[200:203], v[40:43]
	v_mfma_f32_16x16x32_bf16 v[32:35], v[146:149], v[208:211], v[32:35]
	v_mfma_f32_16x16x32_bf16 v[24:27], v[154:157], v[208:211], v[24:27]
	v_mfma_f32_16x16x32_bf16 v[16:19], v[146:149], v[216:219], v[16:19]
	v_mfma_f32_16x16x32_bf16 v[8:11], v[154:157], v[216:219], v[8:11]
	s_setprio 0
	s_setprio 1
	v_mfma_f32_16x16x32_bf16 v[60:63], v[158:161], v[188:191], 0
	v_mfma_f32_16x16x32_bf16 v[52:55], v[170:173], v[188:191], 0
	v_mfma_f32_16x16x32_bf16 v[44:47], v[158:161], v[196:199], 0
	v_mfma_f32_16x16x32_bf16 v[36:39], v[170:173], v[196:199], 0
	v_mfma_f32_16x16x32_bf16 v[28:31], v[158:161], v[204:207], 0
	v_mfma_f32_16x16x32_bf16 v[20:23], v[170:173], v[204:207], 0
	v_mfma_f32_16x16x32_bf16 v[12:15], v[158:161], v[212:215], 0
	v_mfma_f32_16x16x32_bf16 v[4:7], v[170:173], v[212:215], 0
	v_mfma_f32_16x16x32_bf16 v[60:63], v[166:169], v[192:195], v[60:63]
	v_mfma_f32_16x16x32_bf16 v[52:55], v[174:177], v[192:195], v[52:55]
	v_mfma_f32_16x16x32_bf16 v[44:47], v[166:169], v[200:203], v[44:47]
	v_mfma_f32_16x16x32_bf16 v[36:39], v[174:177], v[200:203], v[36:39]
	v_mfma_f32_16x16x32_bf16 v[28:31], v[166:169], v[208:211], v[28:31]
	v_mfma_f32_16x16x32_bf16 v[20:23], v[174:177], v[208:211], v[20:23]
	v_mfma_f32_16x16x32_bf16 v[12:15], v[166:169], v[216:219], v[12:15]
	v_mfma_f32_16x16x32_bf16 v[4:7], v[174:177], v[216:219], v[4:7]
	s_setprio 0
	s_barrier
	v_add_u32_e32 v154, s44, v163
	v_add_u32_e32 v174, s49, v163
	ds_read_b128 v[132:135], v154
	ds_read_b128 v[146:149], v154 offset:1024
	ds_read_b128 v[150:153], v154 offset:2048
	ds_read_b128 v[154:157], v154 offset:3072
	ds_read_b128 v[158:161], v174
	ds_read_b128 v[166:169], v174 offset:1024
	ds_read_b128 v[170:173], v174 offset:2048
	ds_read_b128 v[174:177], v174 offset:3072
	s_add_u32 s28, s28, 0x40000
	s_addc_u32 s29, s29, 0
	s_mov_b32 m0, s42
	v_lshl_add_u64 v[226:227], s[28:29], 0, v[138:139]
	ds_read_b128 v[188:191], v165 offset:32768
	ds_read_b128 v[192:195], v165 offset:33792
	ds_read_b128 v[196:199], v165 offset:34816
	ds_read_b128 v[200:203], v165 offset:35840
	ds_read_b128 v[204:207], v165 offset:36864
	ds_read_b128 v[208:211], v165 offset:37888
	ds_read_b128 v[212:215], v165 offset:38912
	ds_read_b128 v[216:219], v165 offset:39936
	global_load_lds_dwordx4 v[226:227], off
	v_lshl_add_u64 v[226:227], s[28:29], 0, v[136:137]
	s_mov_b32 m0, s43
	s_nop 0
	global_load_lds_dwordx4 v[226:227], off
	s_waitcnt vmcnt(8)
	s_waitcnt lgkmcnt(0)
	s_barrier
	s_setprio 1
	s_waitcnt lgkmcnt(0)
	v_mfma_f32_16x16x32_bf16 v[128:131], v[132:135], v[188:191], v[128:131]
	v_mfma_f32_16x16x32_bf16 v[120:123], v[150:153], v[188:191], v[120:123]
	v_mfma_f32_16x16x32_bf16 v[112:115], v[132:135], v[196:199], v[112:115]
	v_mfma_f32_16x16x32_bf16 v[104:107], v[150:153], v[196:199], v[104:107]
	v_mfma_f32_16x16x32_bf16 v[96:99], v[132:135], v[204:207], v[96:99]
	v_mfma_f32_16x16x32_bf16 v[88:91], v[150:153], v[204:207], v[88:91]
	v_mfma_f32_16x16x32_bf16 v[80:83], v[132:135], v[212:215], v[80:83]
	v_mfma_f32_16x16x32_bf16 v[72:75], v[150:153], v[212:215], v[72:75]
	v_mfma_f32_16x16x32_bf16 v[128:131], v[146:149], v[192:195], v[128:131]
	v_mfma_f32_16x16x32_bf16 v[120:123], v[154:157], v[192:195], v[120:123]
	v_mfma_f32_16x16x32_bf16 v[112:115], v[146:149], v[200:203], v[112:115]
	v_mfma_f32_16x16x32_bf16 v[104:107], v[154:157], v[200:203], v[104:107]
	v_mfma_f32_16x16x32_bf16 v[96:99], v[146:149], v[208:211], v[96:99]
	v_mfma_f32_16x16x32_bf16 v[88:91], v[154:157], v[208:211], v[88:91]
	v_mfma_f32_16x16x32_bf16 v[80:83], v[146:149], v[216:219], v[80:83]
	v_mfma_f32_16x16x32_bf16 v[72:75], v[154:157], v[216:219], v[72:75]
	s_setprio 0
	s_setprio 1
	v_mfma_f32_16x16x32_bf16 v[124:127], v[158:161], v[188:191], v[124:127]
	v_mfma_f32_16x16x32_bf16 v[116:119], v[170:173], v[188:191], v[116:119]
	v_mfma_f32_16x16x32_bf16 v[108:111], v[158:161], v[196:199], v[108:111]
	v_mfma_f32_16x16x32_bf16 v[100:103], v[170:173], v[196:199], v[100:103]
	v_mfma_f32_16x16x32_bf16 v[92:95], v[158:161], v[204:207], v[92:95]
	v_mfma_f32_16x16x32_bf16 v[84:87], v[170:173], v[204:207], v[84:87]
	v_mfma_f32_16x16x32_bf16 v[76:79], v[158:161], v[212:215], v[76:79]
	v_mfma_f32_16x16x32_bf16 v[68:71], v[170:173], v[212:215], v[68:71]
	v_mfma_f32_16x16x32_bf16 v[124:127], v[166:169], v[192:195], v[124:127]
	v_mfma_f32_16x16x32_bf16 v[116:119], v[174:177], v[192:195], v[116:119]
	v_mfma_f32_16x16x32_bf16 v[108:111], v[166:169], v[200:203], v[108:111]
	v_mfma_f32_16x16x32_bf16 v[100:103], v[174:177], v[200:203], v[100:103]
	v_mfma_f32_16x16x32_bf16 v[92:95], v[166:169], v[208:211], v[92:95]
	v_mfma_f32_16x16x32_bf16 v[84:87], v[174:177], v[208:211], v[84:87]
	v_mfma_f32_16x16x32_bf16 v[76:79], v[166:169], v[216:219], v[76:79]
	v_mfma_f32_16x16x32_bf16 v[68:71], v[174:177], v[216:219], v[68:71]
	s_setprio 0
	s_barrier
; #define PG8_STAGE(bufoff, gbase, voff) do { _Pragma("unroll") for (int _i = 0; _i < 2; ++_i) \
;         __builtin_amdgcn_global_load_lds((const unsigned*)((const char*)(gbase) + (voff)[_i]), (PG8_LAS unsigned*)(lds + (bufoff) + ldsw + _i * 8192), 16, 0, 0); } while (0)
; #define PG8_LDA(dst, b, h) do { _Pragma("unroll") for (int m = 0; m < 4; ++m) _Pragma("unroll") for (int k = 0; k < 2; ++k) dst[m][k] = *(const PG8_LAS bf16x8*)(lds + PG8_SA(b, h) + aoff + m * 2048 + k * 1024); } while (0)
; #define PG8_MMA(ai, bj, At, Bt) do { __builtin_amdgcn_s_setprio(1); _Pragma("unroll") for (int m = 0; m < 4; ++m) _Pragma("unroll") for (int n = 0; n < 2; ++n) _Pragma("unroll") for (int k = 0; k < 2; ++k) \
;         acc[ai][bj][m][n] = __builtin_amdgcn_mfma_f32_16x16x32_bf16(Bt[n][k], At[m][k], acc[ai][bj][m][n], 0, 0, 0); __builtin_amdgcn_s_setprio(0); } while (0)
; #define PG8_WAIT_V(n) asm volatile("s_waitcnt vmcnt(" #n ")" ::: "memory")
; #define PG8_WAIT_L(n) asm volatile("s_waitcnt lgkmcnt(" #n ")" ::: "memory")
; #define PG8_BAR __builtin_amdgcn_s_barrier()
; #define PG8_SCHED __builtin_amdgcn_sched_barrier(0)
; template <class Epi, class Sched, bool ALIGN_EPI = false, bool SP2 = false>
; __device__ __forceinline__ void gemm_phase(PG8_LAS unsigned char* lds, const Gemm g, const Sched& S, const Epi& E, const int tid_) {
;     ...
;         for (int t = 0; t < nt; t += 2) {
;             const bool last = (t == nt - 2);
;             const char* a1 = cA + (size_t)(t + 1) * kstep;
;             const char* a2 = last ? nA : cA + (size_t)(t + 2) * kstep; const char* b2 = last ? nB : cB + (size_t)(t + 2) * kstep;
;             const char* a3 = a2 + kstep; const char* b3 = b2 + kstep;
;     ...
;             PG8_LDA(At, 1, 1); PG8_STAGE(PG8_SB(1, 0), b3, voffB); PG8_STAGE(PG8_SB(1, 1), b3 + hstepB, voffB); PG8_STAGE(PG8_SA(1, 0), a3, voffA);
;             PG8_WAIT_V(8); PG8_WAIT_L(0); PG8_BAR; PG8_MMA(1, 0, At, B0); PG8_MMA(1, 1, At, B1); PG8_BAR; PG8_SCHED;
	s_mov_b32 m0, s45
	v_lshl_add_u64 v[178:179], v[178:179], 0, s[96:97]
	s_add_u32 s26, s26, 0x40080
	ds_read_b128 v[188:191], v165 offset:49152
	ds_read_b128 v[192:195], v165 offset:50176
	ds_read_b128 v[196:199], v165 offset:51200
	ds_read_b128 v[200:203], v165 offset:52224
	ds_read_b128 v[204:207], v165 offset:53248
	ds_read_b128 v[208:211], v165 offset:54272
	ds_read_b128 v[212:215], v165 offset:55296
	ds_read_b128 v[216:219], v165 offset:56320
	global_load_lds_dwordx4 v[178:179], off
	v_lshl_add_u64 v[178:179], v[220:221], 0, s[96:97]
	s_mov_b32 m0, s46
	s_addc_u32 s27, s27, 0
	global_load_lds_dwordx4 v[178:179], off
	v_lshl_add_u64 v[178:179], s[26:27], 0, v[2:3]
	s_mov_b32 m0, s50
	s_nop 0
	global_load_lds_dwordx4 v[178:179], off
	v_lshl_add_u64 v[178:179], s[26:27], 0, v[0:1]
	s_mov_b32 m0, s51
	s_nop 0
	global_load_lds_dwordx4 v[178:179], off
	v_lshl_add_u64 v[178:179], v[222:223], 0, s[96:97]
	s_mov_b32 m0, s47
	s_nop 0
	global_load_lds_dwordx4 v[178:179], off
	v_lshl_add_u64 v[178:179], v[224:225], 0, s[96:97]
	s_mov_b32 m0, s48
	s_nop 0
	global_load_lds_dwordx4 v[178:179], off
	s_waitcnt vmcnt(8)
	s_waitcnt lgkmcnt(0)
	s_barrier
	s_setprio 1
	s_waitcnt lgkmcnt(0)
	v_mfma_f32_16x16x32_bf16 v[64:67], v[132:135], v[188:191], v[64:67]
	v_mfma_f32_16x16x32_bf16 v[56:59], v[150:153], v[188:191], v[56:59]
	v_mfma_f32_16x16x32_bf16 v[48:51], v[132:135], v[196:199], v[48:51]
	v_mfma_f32_16x16x32_bf16 v[40:43], v[150:153], v[196:199], v[40:43]
	v_mfma_f32_16x16x32_bf16 v[32:35], v[132:135], v[204:207], v[32:35]
	v_mfma_f32_16x16x32_bf16 v[24:27], v[150:153], v[204:207], v[24:27]
	v_mfma_f32_16x16x32_bf16 v[16:19], v[132:135], v[212:215], v[16:19]
	v_mfma_f32_16x16x32_bf16 v[8:11], v[150:153], v[212:215], v[8:11]
	v_mfma_f32_16x16x32_bf16 v[64:67], v[146:149], v[192:195], v[64:67]
	v_mfma_f32_16x16x32_bf16 v[56:59], v[154:157], v[192:195], v[56:59]
	v_mfma_f32_16x16x32_bf16 v[48:51], v[146:149], v[200:203], v[48:51]
	v_mfma_f32_16x16x32_bf16 v[40:43], v[154:157], v[200:203], v[40:43]
	v_mfma_f32_16x16x32_bf16 v[32:35], v[146:149], v[208:211], v[32:35]
	v_mfma_f32_16x16x32_bf16 v[24:27], v[154:157], v[208:211], v[24:27]
	v_mfma_f32_16x16x32_bf16 v[16:19], v[146:149], v[216:219], v[16:19]
	v_mfma_f32_16x16x32_bf16 v[8:11], v[154:157], v[216:219], v[8:11]
	s_setprio 0
	s_setprio 1
	v_mfma_f32_16x16x32_bf16 v[60:63], v[158:161], v[188:191], v[60:63]
	v_mfma_f32_16x16x32_bf16 v[52:55], v[170:173], v[188:191], v[52:55]
	v_mfma_f32_16x16x32_bf16 v[44:47], v[158:161], v[196:199], v[44:47]
	v_mfma_f32_16x16x32_bf16 v[36:39], v[170:173], v[196:199], v[36:39]
	v_mfma_f32_16x16x32_bf16 v[28:31], v[158:161], v[204:207], v[28:31]
	v_mfma_f32_16x16x32_bf16 v[20:23], v[170:173], v[204:207], v[20:23]
	v_mfma_f32_16x16x32_bf16 v[12:15], v[158:161], v[212:215], v[12:15]
	v_mfma_f32_16x16x32_bf16 v[4:7], v[170:173], v[212:215], v[4:7]
	v_mfma_f32_16x16x32_bf16 v[60:63], v[166:169], v[192:195], v[60:63]
	v_mfma_f32_16x16x32_bf16 v[52:55], v[174:177], v[192:195], v[52:55]
	v_mfma_f32_16x16x32_bf16 v[44:47], v[166:169], v[200:203], v[44:47]
	v_mfma_f32_16x16x32_bf16 v[36:39], v[174:177], v[200:203], v[36:39]
	v_mfma_f32_16x16x32_bf16 v[28:31], v[166:169], v[208:211], v[28:31]
	v_mfma_f32_16x16x32_bf16 v[20:23], v[174:177], v[208:211], v[20:23]
	v_mfma_f32_16x16x32_bf16 v[12:15], v[166:169], v[216:219], v[12:15]
	v_mfma_f32_16x16x32_bf16 v[4:7], v[174:177], v[216:219], v[4:7]
	s_setprio 0
	s_barrier
	s_add_i32 s57, s57, 2
	s_add_u32 s24, s24, 0x100
	s_addc_u32 s25, s25, 0
	s_add_u32 s55, s55, 0x100
	s_addc_u32 s56, s56, 0
